# v38 + Fourier fold items redistributed: workgroups that also run a latent sequence-DFT unit (bx&4==0) fold 2 items, the others 8 (was 5/5); slack probes showed the DFT half is the critical one in the
# baseline (speedup 1.0000x reference)
.LBB0_940:
	s_cmp_le_i32 s88, s4
	s_cselect_b64 s[8:9], -1, 0
	s_and_b64 s[40:41], s[8:9], s[14:15]
	s_andn2_b64 vcc, exec, s[40:41]
	s_mov_b32 s79, s5
	s_cbranch_vccnz .LBB0_1023
	v_readlane_b32 s16, v251, 0
	v_readlane_b32 s22, v251, 6
	v_readlane_b32 s23, v251, 7
	v_mov_b32_e32 v7, v0
	s_mov_b64 s[44:45], s[22:23]
	v_readlane_b32 s20, v251, 4
	v_readlane_b32 s21, v251, 5
	s_mov_b64 s[8:9], s[20:21]
	v_readlane_b32 s56, v251, 10
	v_readlane_b32 s57, v251, 11
	s_mov_b64 s[8:9], s[56:57]
	v_readlane_b32 s58, v251, 12
	v_readlane_b32 s59, v251, 13
	s_mov_b64 s[8:9], s[58:59]
	v_readlane_b32 s60, v251, 14
	v_readlane_b32 s61, v251, 15
	s_mov_b64 s[8:9], s[60:61]
	v_readlane_b32 s62, v251, 16
	v_readlane_b32 s63, v251, 17
	s_mov_b64 s[8:9], s[62:63]
	v_readlane_b32 s64, v251, 18
	v_readlane_b32 s65, v251, 19
	s_mov_b64 s[8:9], s[64:65]
	v_readlane_b32 s66, v251, 20
	v_readlane_b32 s67, v251, 21
	s_mov_b64 s[8:9], s[66:67]
	v_readlane_b32 s68, v251, 22
	v_readlane_b32 s69, v251, 23
	s_mov_b64 s[8:9], s[68:69]
	v_readlane_b32 s70, v251, 24
	v_readlane_b32 s71, v251, 25
	s_mov_b64 s[8:9], s[70:71]
	v_readlane_b32 s56, v251, 26
	v_readlane_b32 s57, v251, 27
	s_mov_b64 s[8:9], s[56:57]
	v_readlane_b32 s58, v251, 28
	v_readlane_b32 s59, v251, 29
	s_mov_b64 s[8:9], s[58:59]
	v_readlane_b32 s60, v251, 30
	v_readlane_b32 s61, v251, 31
	s_mov_b64 s[8:9], s[60:61]
	v_readlane_b32 s62, v251, 32
	v_readlane_b32 s63, v251, 33
	s_mov_b64 s[8:9], s[62:63]
	v_readlane_b32 s64, v251, 34
	v_readlane_b32 s65, v251, 35
	s_mov_b64 s[8:9], s[64:65]
	v_readlane_b32 s66, v251, 36
	v_readlane_b32 s67, v251, 37
	s_mov_b64 s[8:9], s[66:67]
	v_readlane_b32 s68, v251, 38
	v_readlane_b32 s69, v251, 39
	s_mov_b64 s[8:9], s[68:69]
	v_readlane_b32 s70, v251, 40
	v_readlane_b32 s71, v251, 41
	s_mov_b64 s[8:9], s[70:71]
	v_readlane_b32 s56, v251, 42
	v_readlane_b32 s57, v251, 43
	s_mov_b64 s[8:9], s[56:57]
	v_readlane_b32 s58, v251, 44
	v_readlane_b32 s59, v251, 45
	s_mov_b64 s[8:9], s[58:59]
	v_readlane_b32 s60, v251, 46
	v_readlane_b32 s61, v251, 47
	s_mov_b64 s[8:9], s[60:61]
	v_readlane_b32 s62, v251, 48
	v_readlane_b32 s63, v251, 49
	s_mov_b64 s[8:9], s[62:63]
	v_readlane_b32 s64, v251, 50
	v_readlane_b32 s65, v251, 51
	s_mov_b64 s[8:9], s[64:65]
	v_readlane_b32 s66, v251, 52
	v_readlane_b32 s67, v251, 53
	v_readlane_b32 s68, v251, 54
	v_readlane_b32 s69, v251, 55
	s_mov_b64 s[14:15], s[66:67]
	s_mov_b64 s[8:9], s[68:69]
	v_readlane_b32 s70, v251, 56
	v_readlane_b32 s71, v251, 57
	s_mov_b64 s[8:9], s[70:71]
	v_readlane_b32 s17, v251, 1
	s_mov_b64 s[8:9], s[16:17]
	v_ashrrev_i32_e32 v2, 6, v7
	v_readlane_b32 s18, v251, 2
	v_readlane_b32 s19, v251, 3
	v_readfirstlane_b32 s30, v2
	s_mov_b64 s[8:9], s[18:19]
	s_and_b64 vcc, exec, s[38:39]
	s_cbranch_vccnz .LBB0_944
	s_waitcnt lgkmcnt(0)
	v_lshlrev_b32_e32 v3, 3, v7
	v_ashrrev_i32_e32 v12, 3, v7
	v_and_b32_e32 v4, 56, v3
	s_movk_i32 s4, 0x90
	v_mul_lo_u32 v3, v12, s4
	v_lshlrev_b32_e32 v5, 1, v4
	v_add3_u32 v13, 0, v3, v5
	v_lshlrev_b32_e32 v3, 1, v7
	v_lshrrev_b32_e32 v5, 2, v7
	v_and_b32_e32 v3, 24, v3
	v_and_b32_e32 v5, 4, v5
	v_and_b32_e32 v8, 35, v7
	v_or3_b32 v3, v8, v3, v5
	s_movk_i32 s4, 0x480
	s_add_u32 s8, s44, 0x30100000
	v_lshlrev_b32_e32 v8, 3, v2
	v_lshlrev_b32_e32 v3, 1, v3
	v_mul_lo_u32 v2, v2, s4
	s_addc_u32 s9, s45, 0
	v_and_b32_e32 v6, 63, v7
	v_ashrrev_i32_e32 v9, 31, v8
	v_sub_u32_e32 v14, 0, v8
	v_add3_u32 v15, 0, v3, v2
	v_add3_u32 v16, 0, v2, v3
	v_lshlrev_b32_e32 v194, 1, v4
	s_lshr_b32 s18, s2, 3
	s_lshl_b32 s18, s18, 2
	s_and_b32 s100, s2, 3
	s_or_b32 s18, s18, s100
	s_bitcmp1_b32 s2, 2
	s_movk_i32 s101, 0x4ff
	s_cselect_b32 s101, 0x3ff, s101
	s_cselect_b32 s100, 0, 0x400
	s_add_i32 s18, s18, s100
.LBB0_943:
	s_add_i32 s4, s18, 0xfffffc00
	s_cmpk_lt_i32 s18, 0x400
	s_movk_i32 s16, 0x800
	s_cselect_b32 s16, s16, 0x100
	s_mov_b32 s17, 0x50200000
	s_cselect_b32 s4, s18, s4
	s_cselect_b32 s17, s17, 0x51200000
	s_cselect_b32 s19, 12, 9
	s_lshr_b32 s20, s16, 4
	v_cvt_f32_ubyte0_e32 v2, s20
	v_rcp_iflag_f32_e32 v2, v2
	s_sub_i32 s21, 0, s20
	s_abs_i32 s25, s4
	s_ashr_i32 s24, s4, 31
	v_mul_f32_e32 v2, 0x4f7ffffe, v2
	v_cvt_u32_f32_e32 v2, v2
	s_nop 0
	v_readfirstlane_b32 s22, v2
	s_mul_i32 s21, s21, s22
	s_mul_hi_u32 s21, s22, s21
	s_add_i32 s22, s22, s21
	s_mul_hi_u32 s21, s25, s22
	s_mul_i32 s22, s21, s20
	s_sub_i32 s22, s25, s22
	s_add_i32 s23, s21, 1
	s_sub_i32 s26, s22, s20
	s_cmp_ge_u32 s22, s20
	s_cselect_b32 s21, s23, s21
	s_cselect_b32 s22, s26, s22
	s_add_i32 s23, s21, 1
	s_cmp_ge_u32 s22, s20
	s_cselect_b32 s20, s23, s21
	s_xor_b32 s20, s20, s24
	s_sub_i32 s20, s20, s24
	s_ashr_i32 s21, s20, 31
	s_lshl_b64 s[22:23], s[20:21], 11
	s_add_u32 s26, s22, 0x1000
	s_addc_u32 s27, s23, 0
	s_lshl_b64 s[22:23], s[20:21], 8
	s_cmpk_lt_i32 s18, 0x400
	s_cselect_b32 s23, s27, s23
	s_cselect_b32 s22, s26, s22
	s_lshr_b32 s26, s16, 7
	s_ashr_i32 s27, s26, 31
	s_xor_b32 s24, s24, s27
	s_abs_i32 s27, s26
	v_cvt_f32_u32_e32 v2, s27
	s_sub_i32 s28, 0, s27
	v_rcp_iflag_f32_e32 v2, v2
	s_nop 0
	v_mul_f32_e32 v2, 0x4f7ffffe, v2
	v_cvt_u32_f32_e32 v2, v2
	s_nop 0
	v_readfirstlane_b32 s29, v2
	s_mul_i32 s28, s28, s29
	s_mul_hi_u32 s28, s29, s28
	s_add_i32 s29, s29, s28
	s_mul_hi_u32 s28, s25, s29
	s_mul_i32 s29, s28, s27
	s_sub_i32 s25, s25, s29
	s_add_i32 s29, s28, 1
	s_sub_i32 s31, s25, s27
	s_cmp_ge_u32 s25, s27
	s_cselect_b32 s28, s29, s28
	s_cselect_b32 s25, s31, s25
	s_add_i32 s29, s28, 1
	s_cmp_ge_u32 s25, s27
	s_cselect_b32 s25, s29, s28
	s_xor_b32 s25, s25, s24
	s_sub_i32 s25, s25, s24
	s_mul_i32 s24, s25, s26
	s_sub_i32 s4, s4, s24
	s_lshl_b32 s24, s4, 6
	s_lshl_b32 s4, s25, 6
	v_add_u32_e32 v2, s24, v12
	s_and_b32 s25, s4, 0x1c0
	s_lshr_b32 s4, s16, 1
	v_cmp_eq_u32_e32 vcc, 0, v2
	v_sub_u32_e32 v3, s16, v2
	v_mov_b32_e32 v4, s4
	v_cndmask_b32_e32 v4, v3, v4, vcc
	v_ashrrev_i32_e32 v3, 31, v2
	v_lshl_add_u64 v[2:3], s[22:23], 0, v[2:3]
	v_lshlrev_b64 v[2:3], 11, v[2:3]
	v_lshl_add_u64 v[2:3], s[8:9], 0, v[2:3]
	s_lshl_b32 s4, s25, 1
	v_lshl_add_u64 v[2:3], v[2:3], 0, s[4:5]
	v_ashrrev_i32_e32 v5, 31, v4
	v_lshl_add_u64 v[10:11], v[2:3], 0, v[194:195]
	v_lshl_add_u64 v[2:3], s[22:23], 0, v[4:5]
	v_lshlrev_b64 v[2:3], 11, v[2:3]
	v_lshl_add_u64 v[2:3], s[8:9], 0, v[2:3]
	v_lshl_add_u64 v[2:3], v[2:3], 0, s[4:5]
	v_lshl_add_u64 v[18:19], v[2:3], 0, v[194:195]
	global_load_dwordx4 v[2:5], v[10:11], off
	s_add_u32 s22, s44, s17
	s_addc_u32 s23, s45, 0
	s_lshl_b64 s[20:21], s[20:21], 9
	v_cmp_eq_u32_e32 vcc, s24, v14
	s_mov_b32 s17, s5
	s_addk_i32 s18, 0x80
	s_waitcnt vmcnt(0)
	ds_write_b128 v13, v[2:5]
	global_load_dwordx4 v[2:5], v[18:19], off
	s_waitcnt vmcnt(0)
	ds_write_b128 v13, v[2:5] offset:9216
	global_load_dwordx4 v[2:5], v[10:11], off offset:1024
	s_waitcnt vmcnt(0)
	ds_write_b128 v13, v[2:5] offset:18432
	global_load_dwordx4 v[2:5], v[18:19], off offset:1024
	s_waitcnt vmcnt(0)
	ds_write_b128 v13, v[2:5] offset:27648
	s_waitcnt lgkmcnt(0)
	s_barrier
	ds_read_u16 v2, v16 offset:9216
	ds_read_u16 v3, v15
	s_waitcnt lgkmcnt(1)
	v_lshlrev_b32_e32 v17, 16, v2
	s_waitcnt lgkmcnt(0)
	v_lshlrev_b32_e32 v5, 16, v3
	ds_read_u16 v3, v16 offset:18432
	ds_read_u16 v2, v16 offset:27648
	v_add_f32_e32 v22, v17, v5
	s_waitcnt lgkmcnt(1)
	v_lshlrev_b32_e32 v4, 16, v3
	s_waitcnt lgkmcnt(0)
	v_lshlrev_b32_e32 v2, 16, v2
	v_pk_add_f32 v[18:19], v[4:5], v[2:3] neg_lo:[0,1] neg_hi:[0,1]
	ds_read_u16 v2, v16 offset:9504
	ds_read_u16 v3, v15 offset:288
	v_cndmask_b32_e32 v17, v18, v17, vcc
	s_waitcnt lgkmcnt(1)
	v_lshlrev_b32_e32 v10, 16, v2
	ds_read_u16 v4, v16 offset:18720
	ds_read_u16 v2, v16 offset:27936
	s_waitcnt lgkmcnt(2)
	v_lshlrev_b32_e32 v3, 16, v3
	v_add_f32_e32 v19, v10, v3
	s_waitcnt lgkmcnt(1)
	v_lshlrev_b32_e32 v4, 16, v4
	s_waitcnt lgkmcnt(0)
	v_lshlrev_b32_e32 v2, 16, v2
	v_pk_add_f32 v[20:21], v[4:5], v[2:3] neg_lo:[0,1] neg_hi:[0,1]
	v_or_b32_e32 v2, s20, v6
	v_mov_b32_e32 v3, s21
	v_or_b32_e32 v2, s25, v2
	v_lshlrev_b64 v[2:3], s19, v[2:3]
	v_lshl_add_u64 v[2:3], s[22:23], 0, v[2:3]
	s_ashr_i32 s25, s24, 31
	v_lshl_add_u64 v[2:3], s[24:25], 1, v[2:3]
	v_lshl_add_u64 v[10:11], v[8:9], 1, v[2:3]
	v_cndmask_b32_e32 v21, v22, v5, vcc
	ds_read_u16 v2, v15 offset:144
	ds_read_u16 v3, v15 offset:432
	ds_read_u16 v4, v16 offset:9360
	ds_read_u16 v5, v16 offset:9648
	s_cmp_gt_i32 s18, s101
	s_waitcnt lgkmcnt(3)
	v_lshlrev_b32_e32 v2, 16, v2
	s_waitcnt lgkmcnt(2)
	v_lshlrev_b32_e32 v3, 16, v3
	s_waitcnt lgkmcnt(0)
	v_lshlrev_b32_e32 v5, 16, v5
	v_lshlrev_b32_e32 v4, 16, v4
	v_pk_add_f32 v[2:3], v[2:3], v[4:5]
	ds_read_u16 v4, v15 offset:576
	ds_read_u16 v5, v15 offset:864
	ds_read_u16 v22, v16 offset:9792
	ds_read_u16 v23, v16 offset:10080
	v_bfe_u32 v27, v3, 16, 1
	v_add3_u32 v3, v3, v27, s54
	s_waitcnt lgkmcnt(3)
	v_lshlrev_b32_e32 v4, 16, v4
	s_waitcnt lgkmcnt(2)
	v_lshlrev_b32_e32 v5, 16, v5
	s_waitcnt lgkmcnt(0)
	v_lshlrev_b32_e32 v23, 16, v23
	v_lshlrev_b32_e32 v22, 16, v22
	v_pk_add_f32 v[4:5], v[4:5], v[22:23]
	ds_read_u16 v22, v15 offset:720
	ds_read_u16 v23, v15 offset:1008
	ds_read_u16 v24, v16 offset:9936
	ds_read_u16 v25, v16 offset:10224
	v_bfe_u32 v27, v19, 16, 1
	v_add3_u32 v19, v19, v27, s54
	s_waitcnt lgkmcnt(3)
	v_lshlrev_b32_e32 v22, 16, v22
	s_waitcnt lgkmcnt(2)
	v_lshlrev_b32_e32 v23, 16, v23
	s_waitcnt lgkmcnt(0)
	v_lshlrev_b32_e32 v25, 16, v25
	v_lshlrev_b32_e32 v24, 16, v24
	v_pk_add_f32 v[22:23], v[22:23], v[24:25]
	v_bfe_u32 v24, v2, 16, 1
	v_bfe_u32 v25, v23, 16, 1
	v_bfe_u32 v26, v22, 16, 1
	v_add3_u32 v22, v22, v26, s54
	v_add3_u32 v23, v23, v25, s54
	v_add3_u32 v2, v2, v24, s54
	v_bfe_u32 v24, v21, 16, 1
	v_bfe_u32 v25, v4, 16, 1
	v_bfe_u32 v26, v5, 16, 1
	v_add3_u32 v21, v21, v24, s54
	v_add3_u32 v5, v5, v26, s54
	v_add3_u32 v4, v4, v25, s54
	v_lshrrev_b32_e32 v21, 16, v21
	v_lshrrev_b32_e32 v4, 16, v4
	v_lshrrev_b32_e32 v5, 16, v5
	v_lshrrev_b32_e32 v19, 16, v19
	v_and_or_b32 v2, v2, s6, v21
	v_and_or_b32 v5, v23, s6, v5
	v_and_or_b32 v4, v22, s6, v4
	v_and_or_b32 v3, v3, s6, v19
	ds_read_u16 v19, v16 offset:18576
	ds_read_u16 v21, v16 offset:18864
	ds_read_u16 v22, v16 offset:27792
	ds_read_u16 v23, v16 offset:28080
	ds_read_u16 v24, v16 offset:19008
	ds_read_u16 v25, v16 offset:19296
	ds_read_u16 v26, v16 offset:28224
	ds_read_u16 v27, v16 offset:28512
	ds_read_u16 v28, v16 offset:19152
	ds_read_u16 v29, v16 offset:19440
	ds_read_u16 v30, v16 offset:28368
	ds_read_u16 v31, v16 offset:28656
	global_store_dwordx4 v[10:11], v[2:5], off
	s_waitcnt lgkmcnt(5)
	v_lshlrev_b32_e32 v18, 16, v26
	v_lshl_add_u64 v[10:11], v[10:11], 0, s[16:17]
	v_lshlrev_b32_e32 v3, 16, v21
	v_lshlrev_b32_e32 v2, 16, v19
	v_lshlrev_b32_e32 v5, 16, v23
	v_lshlrev_b32_e32 v4, 16, v22
	v_pk_add_f32 v[2:3], v[2:3], v[4:5] neg_lo:[0,1] neg_hi:[0,1]
	v_lshlrev_b32_e32 v5, 16, v25
	v_lshlrev_b32_e32 v4, 16, v24
	s_waitcnt lgkmcnt(4)
	v_lshlrev_b32_e32 v19, 16, v27
	v_pk_add_f32 v[4:5], v[4:5], v[18:19] neg_lo:[0,1] neg_hi:[0,1]
	s_waitcnt lgkmcnt(2)
	v_lshlrev_b32_e32 v19, 16, v29
	v_lshlrev_b32_e32 v18, 16, v28
	s_waitcnt lgkmcnt(0)
	v_lshlrev_b32_e32 v23, 16, v31
	v_lshlrev_b32_e32 v22, 16, v30
	v_pk_add_f32 v[18:19], v[18:19], v[22:23] neg_lo:[0,1] neg_hi:[0,1]
	v_bfe_u32 v21, v2, 16, 1
	v_bfe_u32 v22, v19, 16, 1
	v_bfe_u32 v23, v18, 16, 1
	v_bfe_u32 v24, v3, 16, 1
	v_add3_u32 v3, v3, v24, s54
	v_add3_u32 v18, v18, v23, s54
	v_add3_u32 v19, v19, v22, s54
	v_add3_u32 v2, v2, v21, s54
	v_bfe_u32 v21, v17, 16, 1
	v_bfe_u32 v22, v4, 16, 1
	v_bfe_u32 v23, v5, 16, 1
	v_bfe_u32 v24, v20, 16, 1
	v_add3_u32 v17, v17, v21, s54
	v_add3_u32 v5, v5, v23, s54
	v_add3_u32 v4, v4, v22, s54
	v_add3_u32 v20, v20, v24, s54
	v_lshrrev_b32_e32 v17, 16, v17
	v_lshrrev_b32_e32 v4, 16, v4
	v_lshrrev_b32_e32 v5, 16, v5
	v_lshrrev_b32_e32 v20, 16, v20
	v_and_or_b32 v2, v2, s6, v17
	v_and_or_b32 v5, v19, s6, v5
	v_and_or_b32 v4, v18, s6, v4
	v_and_or_b32 v3, v3, s6, v20
	global_store_dwordx4 v[10:11], v[2:5], off
	s_barrier
	s_cbranch_scc0 .LBB0_943
